# GEMM<0>/<1> last partial tile round taken in blockIdx order (leftover tiles spread over all XCDs)
# speedup vs baseline: 1.0024x; 1.0024x over previous
.LBB0_908:
	s_add_i32 s2, s7, s8
	s_cmpk_lg_i32 s7, 0x200
	s_cbranch_scc1 .Ltl910_n
	v_readlane_b32 s2, v253, 36
	s_nop 0
	s_add_i32 s2, s7, s2
.Ltl910_n:
	s_cmpk_gt_i32 s2, 0x207
	s_mov_b64 s[0:1], -1
	s_cbranch_scc1 .LBB0_907
	s_ashr_i32 s0, s2, 31
	s_lshr_b32 s0, s0, 27
	s_add_i32 s0, s2, s0
	s_ashr_i32 s1, s0, 5
	s_lshl_b32 s1, s1, 3
	s_sub_i32 s3, 0x82, s1
	s_min_u32 s3, s3, 8
	v_cvt_f32_ubyte0_e32 v0, s3
	v_rcp_iflag_f32_e32 v0, v0
	s_sub_i32 s5, 0, s3
	s_andn2_b32 s0, s0, 31
	s_sub_i32 s0, s2, s0
	v_mul_f32_e32 v0, 0x4f7ffffe, v0
	v_cvt_u32_f32_e32 v0, v0
	s_abs_i32 s4, s0
	s_ashr_i32 s2, s0, 31
	s_waitcnt vmcnt(63) expcnt(7) lgkmcnt(15)
	v_readfirstlane_b32 s10, v0
	s_mul_i32 s5, s5, s10
	s_mul_hi_u32 s5, s10, s5
	s_add_i32 s10, s10, s5
	s_mul_hi_u32 s5, s4, s10
	s_mul_i32 s10, s5, s3
	s_sub_i32 s4, s4, s10
	s_add_i32 s10, s5, 1
	s_sub_i32 s11, s4, s3
	s_cmp_ge_u32 s4, s3
	s_cselect_b32 s5, s10, s5
	s_cselect_b32 s4, s11, s4
	s_add_i32 s10, s5, 1
	s_cmp_ge_u32 s4, s3
	s_cselect_b32 s4, s10, s5
	s_xor_b32 s4, s4, s2
	s_sub_i32 s2, s4, s2
	s_mul_i32 s3, s2, s3
	s_sub_i32 s0, s0, s3
	s_add_i32 s0, s0, s1
	s_lshl_b32 s0, s0, 8
	s_lshl_b32 s2, s2, 8
	s_ashr_i32 s1, s0, 31
	s_ashr_i32 s3, s2, 31
	s_lshl_b64 s[4:5], s[0:1], 11
	s_lshl_b64 s[10:11], s[2:3], 11
	s_add_u32 s12, s64, s4
	v_mov_b32_e32 v0, v132
	s_addc_u32 s13, s65, s5
	s_barrier
	v_readlane_b32 s14, v251, 50
	v_lshl_add_u64 v[2:3], v[0:1], 1, s[12:13]
	v_add_u32_e32 v0, 32, v133
	v_readlane_b32 s15, v251, 51
	v_readfirstlane_b32 s1, v0
	s_mov_b32 m0, s1
	v_mov_b32_e32 v0, v134
	global_load_lds_dwordx4 v[2:3], off
	s_add_u32 s14, s14, s10
	v_lshl_add_u64 v[2:3], v[0:1], 1, s[12:13]
	v_add_u32_e32 v0, 32, v135
	s_addc_u32 s15, s15, s11
	v_readfirstlane_b32 s1, v0
	s_mov_b32 m0, s1
	v_mov_b32_e32 v0, v136
	global_load_lds_dwordx4 v[2:3], off
	v_readlane_b32 s3, v254, 3
	v_lshl_add_u64 v[2:3], v[0:1], 1, s[12:13]
	v_add_u32_e32 v0, 32, v137
	s_mov_b32 s9, 0
	v_readfirstlane_b32 s1, v0
	s_mov_b32 m0, s1
	v_mov_b32_e32 v0, v138
	global_load_lds_dwordx4 v[2:3], off
	s_nop 0
	v_lshl_add_u64 v[2:3], v[0:1], 1, s[12:13]
	v_add_u32_e32 v0, 32, v139
	s_nop 0
	v_readfirstlane_b32 s1, v0
	s_mov_b32 m0, s1
	v_mov_b32_e32 v0, v132
	global_load_lds_dwordx4 v[2:3], off
	s_nop 0
	v_lshl_add_u64 v[2:3], v[0:1], 1, s[14:15]
	v_add_u32_e32 v0, s3, v133
	s_nop 0
	v_readfirstlane_b32 s1, v0
	s_mov_b32 m0, s1
	v_mov_b32_e32 v0, v134
	global_load_lds_dwordx4 v[2:3], off
	s_nop 0
	v_lshl_add_u64 v[2:3], v[0:1], 1, s[14:15]
	v_add_u32_e32 v0, s3, v135
	s_nop 0
	v_readfirstlane_b32 s1, v0
	s_mov_b32 m0, s1
	v_mov_b32_e32 v0, v136
	global_load_lds_dwordx4 v[2:3], off
	s_nop 0
	v_lshl_add_u64 v[2:3], v[0:1], 1, s[14:15]
	v_add_u32_e32 v0, s3, v137
	s_nop 0
	v_readfirstlane_b32 s1, v0
	s_mov_b32 m0, s1
	v_mov_b32_e32 v0, v138
	global_load_lds_dwordx4 v[2:3], off
	s_nop 0
	v_lshl_add_u64 v[2:3], v[0:1], 1, s[14:15]
	v_add_u32_e32 v0, s3, v139
	v_readlane_b32 s3, v253, 26
	v_readfirstlane_b32 s1, v0
	s_mov_b32 m0, s1
	v_readlane_b32 s1, v253, 25
	global_load_lds_dwordx4 v[2:3], off
	s_add_u32 s1, s1, s4
	s_waitcnt vmcnt(0)
	s_addc_u32 s3, s3, s5
	v_readlane_b32 s4, v253, 34
	s_add_u32 s10, s4, s10
	v_readlane_b32 s4, v253, 35
	v_mov_b32_e32 v2, 0
	s_addc_u32 s11, s4, s11
	s_mov_b64 s[4:5], 0
	v_mov_b32_e32 v3, v2
	v_mov_b32_e32 v4, v2
	v_mov_b32_e32 v5, v2
	v_mov_b32_e32 v6, v2
	v_mov_b32_e32 v7, v2
	v_mov_b32_e32 v8, v2
	v_mov_b32_e32 v9, v2
	v_mov_b32_e32 v10, v2
	v_mov_b32_e32 v11, v2
	v_mov_b32_e32 v12, v2
	v_mov_b32_e32 v13, v2
	s_waitcnt vmcnt(0)
	v_mov_b32_e32 v14, v2
	v_mov_b32_e32 v15, v2
	v_mov_b32_e32 v16, v2
	v_mov_b32_e32 v17, v2
	v_mov_b32_e32 v18, v2
	v_mov_b32_e32 v19, v2
	v_mov_b32_e32 v20, v2
	v_mov_b32_e32 v21, v2
	v_mov_b32_e32 v22, v2
	v_mov_b32_e32 v23, v2
	v_mov_b32_e32 v24, v2
	v_mov_b32_e32 v25, v2
	v_mov_b32_e32 v26, v2
	v_mov_b32_e32 v27, v2
	v_mov_b32_e32 v28, v2
	v_mov_b32_e32 v29, v2
	v_mov_b32_e32 v30, v2
	v_mov_b32_e32 v31, v2
	v_mov_b32_e32 v32, v2
	v_mov_b32_e32 v33, v2
	v_mov_b32_e32 v34, v2
	v_mov_b32_e32 v35, v2
	v_mov_b32_e32 v36, v2
	v_mov_b32_e32 v37, v2
	v_mov_b32_e32 v38, v2
	v_mov_b32_e32 v39, v2
	v_mov_b32_e32 v40, v2
	v_mov_b32_e32 v41, v2
	v_mov_b32_e32 v42, v2
	v_mov_b32_e32 v43, v2
	v_mov_b32_e32 v44, v2
	v_mov_b32_e32 v45, v2
	v_mov_b32_e32 v46, v2
	v_mov_b32_e32 v47, v2
	v_mov_b32_e32 v48, v2
	v_mov_b32_e32 v49, v2
	v_mov_b32_e32 v50, v2
	v_mov_b32_e32 v51, v2
	v_mov_b32_e32 v52, v2
	v_mov_b32_e32 v53, v2
	v_mov_b32_e32 v54, v2
	v_mov_b32_e32 v55, v2
	v_mov_b32_e32 v56, v2
	v_mov_b32_e32 v57, v2
	v_mov_b32_e32 v58, v2
	v_mov_b32_e32 v59, v2
	v_mov_b32_e32 v60, v2
	v_mov_b32_e32 v61, v2
	v_mov_b32_e32 v62, v2
	v_mov_b32_e32 v63, v2
	v_mov_b32_e32 v64, v2
	v_mov_b32_e32 v65, v2
	v_mov_b32_e32 v66, v2
	v_mov_b32_e32 v67, v2
	v_mov_b32_e32 v68, v2
	v_mov_b32_e32 v69, v2
	v_mov_b32_e32 v70, v2
	v_mov_b32_e32 v71, v2
	v_mov_b32_e32 v72, v2
	v_mov_b32_e32 v73, v2
	v_mov_b32_e32 v74, v2
	v_mov_b32_e32 v75, v2
	v_mov_b32_e32 v76, v2
	v_mov_b32_e32 v77, v2
	v_mov_b32_e32 v78, v2
	v_mov_b32_e32 v79, v2
	v_mov_b32_e32 v80, v2
	v_mov_b32_e32 v81, v2
	v_mov_b32_e32 v82, v2
	v_mov_b32_e32 v83, v2
	v_mov_b32_e32 v84, v2
	v_mov_b32_e32 v85, v2
	v_mov_b32_e32 v86, v2
	v_mov_b32_e32 v87, v2
	v_mov_b32_e32 v88, v2
	v_mov_b32_e32 v89, v2
	v_mov_b32_e32 v90, v2
	v_mov_b32_e32 v91, v2
	v_mov_b32_e32 v92, v2
	v_mov_b32_e32 v93, v2
	v_mov_b32_e32 v94, v2
	v_mov_b32_e32 v95, v2
	v_mov_b32_e32 v96, v2
	v_mov_b32_e32 v97, v2
	v_mov_b32_e32 v98, v2
	v_mov_b32_e32 v99, v2
	v_mov_b32_e32 v100, v2
	v_mov_b32_e32 v101, v2
	v_mov_b32_e32 v102, v2
	v_mov_b32_e32 v103, v2
	v_mov_b32_e32 v104, v2
	v_mov_b32_e32 v105, v2
	v_mov_b32_e32 v106, v2
	v_mov_b32_e32 v107, v2
	v_mov_b32_e32 v108, v2
	v_mov_b32_e32 v109, v2
	v_mov_b32_e32 v110, v2
	v_mov_b32_e32 v111, v2
	v_mov_b32_e32 v112, v2
	v_mov_b32_e32 v113, v2
	v_mov_b32_e32 v114, v2
	v_mov_b32_e32 v115, v2
	v_mov_b32_e32 v116, v2
	v_mov_b32_e32 v117, v2
	v_mov_b32_e32 v118, v2
	v_mov_b32_e32 v119, v2
	v_mov_b32_e32 v120, v2
	v_mov_b32_e32 v121, v2
	v_mov_b32_e32 v122, v2
	v_mov_b32_e32 v123, v2
	v_mov_b32_e32 v124, v2
	v_mov_b32_e32 v125, v2
	v_mov_b32_e32 v126, v2
	v_mov_b32_e32 v127, v2
	v_mov_b32_e32 v128, v2
	v_mov_b32_e32 v129, v2
	s_waitcnt lgkmcnt(0)
	s_barrier
	v_lshlrev_b32_e32 v149, 1, v132
	v_readfirstlane_b32 s14, v133
	v_add_u32_e32 v205, v140, v142
	v_add_u32_e32 v209, v141, v142
	v_add_u32_e32 v206, v140, v146
	v_add_u32_e32 v210, v141, v146
	v_add_u32_e32 v207, v140, v147
	v_add_u32_e32 v211, v141, v147
	v_add_u32_e32 v208, v140, v148
	v_add_u32_e32 v212, v141, v148
	s_mov_b32 s9, 7
	s_add_u32 m0, s14, 0x8020
	s_add_u32 s12, s1, s4
	s_addc_u32 s13, s3, s5
	global_load_lds_dwordx4 v149, s[12:13]
	s_add_u32 m0, s14, 0xa020
	s_add_u32 s12, s12, 0x20000
	s_addc_u32 s13, s13, 0
	global_load_lds_dwordx4 v149, s[12:13]
	s_add_u32 m0, s14, 0xc020
	s_add_u32 s12, s12, 0x20000
	s_addc_u32 s13, s13, 0
	global_load_lds_dwordx4 v149, s[12:13]
	s_add_u32 m0, s14, 0xe020
	s_add_u32 s12, s12, 0x20000
	s_addc_u32 s13, s13, 0
	global_load_lds_dwordx4 v149, s[12:13]
	s_add_u32 m0, s14, 0x18020
	s_add_u32 s12, s10, s4
	s_addc_u32 s13, s11, s5
	global_load_lds_dwordx4 v149, s[12:13]
	ds_read_b128 v[150:153], v205 offset:0
	ds_read_b128 v[166:169], v209 offset:0
	ds_read_b128 v[170:173], v209 offset:4096
	ds_read_b128 v[154:157], v205 offset:4096
	ds_read_b128 v[158:161], v205 offset:8192
	ds_read_b128 v[162:165], v205 offset:12288

.LBB0_1120:
	s_add_i32 s2, s13, s14
	s_cmpk_lg_i32 s13, 0x800
	s_cbranch_scc1 .Ltl1122_n
	v_readlane_b32 s2, v253, 36
	s_nop 0
	s_add_i32 s2, s13, s2
.Ltl1122_n:
	s_cmpk_gt_i32 s2, 0x81f
	s_mov_b64 s[0:1], -1
	s_cbranch_scc1 .LBB0_1119
	s_ashr_i32 s0, s2, 31
	s_lshr_b32 s0, s0, 25
	s_add_i32 s0, s2, s0
	s_ashr_i32 s1, s0, 7
	s_lshl_b32 s1, s1, 3
	s_sub_i32 s3, 0x82, s1
	s_min_u32 s3, s3, 8
	v_cvt_f32_ubyte0_e32 v0, s3
	v_rcp_iflag_f32_e32 v0, v0
	s_sub_i32 s6, 0, s3
	s_and_b32 s0, s0, 0xffffff80
	s_sub_i32 s0, s2, s0
	v_mul_f32_e32 v0, 0x4f7ffffe, v0
	v_cvt_u32_f32_e32 v0, v0
	s_abs_i32 s4, s0
	s_ashr_i32 s2, s0, 31
	s_waitcnt vmcnt(63) expcnt(7) lgkmcnt(15)
	v_readfirstlane_b32 s7, v0
	s_mul_i32 s6, s6, s7
	s_mul_hi_u32 s6, s7, s6
	s_add_i32 s7, s7, s6
	s_mul_hi_u32 s6, s4, s7
	s_mul_i32 s7, s6, s3
	s_sub_i32 s4, s4, s7
	s_add_i32 s7, s6, 1
	s_sub_i32 s8, s4, s3
	s_cmp_ge_u32 s4, s3
	s_cselect_b32 s6, s7, s6
	s_cselect_b32 s4, s8, s4
	s_add_i32 s7, s6, 1
	s_cmp_ge_u32 s4, s3
	s_cselect_b32 s4, s7, s6
	s_xor_b32 s4, s4, s2
	s_sub_i32 s4, s4, s2
	s_mul_i32 s2, s4, s3
	s_sub_i32 s0, s0, s2
	s_add_i32 s0, s0, s1
	s_lshl_b32 s0, s0, 8
	s_lshl_b32 s6, s4, 8
	s_ashr_i32 s1, s0, 31
	s_ashr_i32 s7, s6, 31
	s_lshl_b64 s[2:3], s[0:1], 11
	s_lshl_b64 s[8:9], s[6:7], 11
	s_add_u32 s10, s64, s2
	v_mov_b32_e32 v0, v143
	s_addc_u32 s11, s65, s3
	s_barrier
	v_readlane_b32 s16, v251, 2
	v_lshl_add_u64 v[2:3], v[0:1], 1, s[10:11]
	v_add_u32_e32 v0, 32, v158
	v_readlane_b32 s30, v251, 16
	v_readfirstlane_b32 s1, v0
	s_mov_b32 m0, s1
	v_mov_b32_e32 v0, v159
	global_load_lds_dwordx4 v[2:3], off
	v_readlane_b32 s17, v251, 3
	v_lshl_add_u64 v[2:3], v[0:1], 1, s[10:11]
	v_add_u32_e32 v0, 32, v160
	v_readlane_b32 s31, v251, 17
	v_readfirstlane_b32 s1, v0
	s_mov_b32 m0, s1
	v_mov_b32_e32 v0, v161
	global_load_lds_dwordx4 v[2:3], off
	s_add_u32 s16, s30, s8
	v_lshl_add_u64 v[2:3], v[0:1], 1, s[10:11]
	v_add_u32_e32 v0, 32, v162
	s_addc_u32 s17, s31, s9
	v_readfirstlane_b32 s1, v0
	s_mov_b32 m0, s1
	v_mov_b32_e32 v0, v163
	global_load_lds_dwordx4 v[2:3], off
	v_readlane_b32 s7, v254, 3
	v_lshl_add_u64 v[2:3], v[0:1], 1, s[10:11]
	v_add_u32_e32 v0, 32, v164
	s_mov_b32 s5, 0
	v_readfirstlane_b32 s1, v0
	s_mov_b32 m0, s1
	v_mov_b32_e32 v0, v143
	global_load_lds_dwordx4 v[2:3], off
	v_readlane_b32 s18, v251, 4
	v_lshl_add_u64 v[2:3], v[0:1], 1, s[16:17]
	v_add_u32_e32 v0, s7, v158
	v_readlane_b32 s19, v251, 5
	v_readfirstlane_b32 s1, v0
	s_mov_b32 m0, s1
	v_mov_b32_e32 v0, v159
	global_load_lds_dwordx4 v[2:3], off
	v_readlane_b32 s20, v251, 6
	v_lshl_add_u64 v[2:3], v[0:1], 1, s[16:17]
	v_add_u32_e32 v0, s7, v160
	v_readlane_b32 s21, v251, 7
	v_readfirstlane_b32 s1, v0
	s_mov_b32 m0, s1
	v_mov_b32_e32 v0, v161
	global_load_lds_dwordx4 v[2:3], off
	v_readlane_b32 s22, v251, 8
	v_lshl_add_u64 v[2:3], v[0:1], 1, s[16:17]
	v_add_u32_e32 v0, s7, v162
	v_readlane_b32 s23, v251, 9
	v_readfirstlane_b32 s1, v0
	s_mov_b32 m0, s1
	v_mov_b32_e32 v0, v163
	global_load_lds_dwordx4 v[2:3], off
	v_readlane_b32 s24, v251, 10
	v_lshl_add_u64 v[2:3], v[0:1], 1, s[16:17]
	v_add_u32_e32 v0, s7, v164
	v_readlane_b32 s25, v251, 11
	v_readfirstlane_b32 s1, v0
	s_mov_b32 m0, s1
	v_readlane_b32 s1, v253, 25
	global_load_lds_dwordx4 v[2:3], off
	s_add_u32 s1, s1, s2
	v_readlane_b32 s2, v253, 26
	s_waitcnt vmcnt(0)
	s_addc_u32 s7, s2, s3
	v_readlane_b32 s2, v253, 45
	s_add_u32 s8, s2, s8
	v_readlane_b32 s2, v253, 46
	v_mov_b32_e32 v2, 0
	s_addc_u32 s9, s2, s9
	s_mov_b64 s[2:3], 0
	v_mov_b32_e32 v3, v2
	v_mov_b32_e32 v4, v2
	v_mov_b32_e32 v5, v2
	v_mov_b32_e32 v6, v2
	v_mov_b32_e32 v7, v2
	v_mov_b32_e32 v8, v2
	v_mov_b32_e32 v9, v2
	v_mov_b32_e32 v10, v2
	v_mov_b32_e32 v11, v2
	v_mov_b32_e32 v12, v2
	v_mov_b32_e32 v13, v2
	s_waitcnt vmcnt(0)
	v_mov_b32_e32 v14, v2
	v_mov_b32_e32 v15, v2
	v_mov_b32_e32 v16, v2
	v_mov_b32_e32 v17, v2
	v_mov_b32_e32 v18, v2
	v_mov_b32_e32 v19, v2
	v_mov_b32_e32 v20, v2
	v_mov_b32_e32 v21, v2
	v_mov_b32_e32 v22, v2
	v_mov_b32_e32 v23, v2
	v_mov_b32_e32 v24, v2
	v_mov_b32_e32 v25, v2
	v_mov_b32_e32 v26, v2
	v_mov_b32_e32 v27, v2
	v_mov_b32_e32 v28, v2
	v_mov_b32_e32 v29, v2
	v_mov_b32_e32 v30, v2
	v_mov_b32_e32 v31, v2
	v_mov_b32_e32 v32, v2
	v_mov_b32_e32 v33, v2
	v_mov_b32_e32 v34, v2
	v_mov_b32_e32 v35, v2
	v_mov_b32_e32 v36, v2
	v_mov_b32_e32 v37, v2
	v_mov_b32_e32 v38, v2
	v_mov_b32_e32 v39, v2
	v_mov_b32_e32 v40, v2
	v_mov_b32_e32 v41, v2
	v_mov_b32_e32 v42, v2
	v_mov_b32_e32 v43, v2
	v_mov_b32_e32 v44, v2
	v_mov_b32_e32 v45, v2
	v_mov_b32_e32 v46, v2
	v_mov_b32_e32 v47, v2
	v_mov_b32_e32 v48, v2
	v_mov_b32_e32 v49, v2
	v_mov_b32_e32 v50, v2
	v_mov_b32_e32 v51, v2
	v_mov_b32_e32 v52, v2
	v_mov_b32_e32 v53, v2
	v_mov_b32_e32 v54, v2
	v_mov_b32_e32 v55, v2
	v_mov_b32_e32 v56, v2
	v_mov_b32_e32 v57, v2
	v_mov_b32_e32 v58, v2
	v_mov_b32_e32 v59, v2
	v_mov_b32_e32 v60, v2
	v_mov_b32_e32 v61, v2
	v_mov_b32_e32 v62, v2
	v_mov_b32_e32 v63, v2
	v_mov_b32_e32 v64, v2
	v_mov_b32_e32 v65, v2
	v_mov_b32_e32 v66, v2
	v_mov_b32_e32 v67, v2
	v_mov_b32_e32 v68, v2
	v_mov_b32_e32 v69, v2
	v_mov_b32_e32 v70, v2
	v_mov_b32_e32 v71, v2
	v_mov_b32_e32 v72, v2
	v_mov_b32_e32 v73, v2
	v_mov_b32_e32 v74, v2
	v_mov_b32_e32 v75, v2
	v_mov_b32_e32 v76, v2
	v_mov_b32_e32 v77, v2
	v_mov_b32_e32 v78, v2
	v_mov_b32_e32 v79, v2
	v_mov_b32_e32 v80, v2
	v_mov_b32_e32 v81, v2
	v_mov_b32_e32 v82, v2
	v_mov_b32_e32 v83, v2
	v_mov_b32_e32 v84, v2
	v_mov_b32_e32 v85, v2
	v_mov_b32_e32 v86, v2
	v_mov_b32_e32 v87, v2
	v_mov_b32_e32 v88, v2
	v_mov_b32_e32 v89, v2
	v_mov_b32_e32 v90, v2
	v_mov_b32_e32 v91, v2
	v_mov_b32_e32 v92, v2
	v_mov_b32_e32 v93, v2
	v_mov_b32_e32 v94, v2
	v_mov_b32_e32 v95, v2
	v_mov_b32_e32 v96, v2
	v_mov_b32_e32 v97, v2
	v_mov_b32_e32 v98, v2
	v_mov_b32_e32 v99, v2
	v_mov_b32_e32 v100, v2
	v_mov_b32_e32 v101, v2
	v_mov_b32_e32 v102, v2
	v_mov_b32_e32 v103, v2
	v_mov_b32_e32 v104, v2
	v_mov_b32_e32 v105, v2
	v_mov_b32_e32 v106, v2
	v_mov_b32_e32 v107, v2
	v_mov_b32_e32 v108, v2
	v_mov_b32_e32 v109, v2
	v_mov_b32_e32 v110, v2
	v_mov_b32_e32 v111, v2
	v_mov_b32_e32 v112, v2
	v_mov_b32_e32 v113, v2
	v_mov_b32_e32 v114, v2
	v_mov_b32_e32 v115, v2
	v_mov_b32_e32 v116, v2
	v_mov_b32_e32 v117, v2
	v_mov_b32_e32 v118, v2
	v_mov_b32_e32 v119, v2
	v_mov_b32_e32 v120, v2
	v_mov_b32_e32 v121, v2
	v_mov_b32_e32 v122, v2
	v_mov_b32_e32 v123, v2
	v_mov_b32_e32 v124, v2
	v_mov_b32_e32 v125, v2
	v_mov_b32_e32 v126, v2
	v_mov_b32_e32 v127, v2
	v_mov_b32_e32 v128, v2
	v_mov_b32_e32 v129, v2
	v_readlane_b32 s26, v251, 12
	v_readlane_b32 s27, v251, 13
	v_readlane_b32 s28, v251, 14
	v_readlane_b32 s29, v251, 15
	s_waitcnt lgkmcnt(0)
	s_barrier
	v_lshlrev_b32_e32 v142, 1, v143
	v_readfirstlane_b32 s15, v158
	v_add_u32_e32 v156, v165, v167
	v_add_u32_e32 v195, v166, v167
	v_add_u32_e32 v157, v165, v172
	v_add_u32_e32 v200, v166, v172
	v_add_u32_e32 v193, v165, v173
	v_add_u32_e32 v201, v166, v173
	v_add_u32_e32 v194, v165, v174
	v_add_u32_e32 v202, v166, v174
	s_mov_b32 s5, 7
	s_add_u32 m0, s15, 0x8020
	s_add_u32 s10, s1, s2
	s_addc_u32 s11, s7, s3
	global_load_lds_dwordx4 v142, s[10:11]
	s_add_u32 m0, s15, 0xa020
	s_add_u32 s10, s10, 0x20000
	s_addc_u32 s11, s11, 0
	global_load_lds_dwordx4 v142, s[10:11]
	s_add_u32 m0, s15, 0xc020
	s_add_u32 s10, s10, 0x20000
	s_addc_u32 s11, s11, 0
	global_load_lds_dwordx4 v142, s[10:11]
	s_add_u32 m0, s15, 0xe020
	s_add_u32 s10, s10, 0x20000
	s_addc_u32 s11, s11, 0
	global_load_lds_dwordx4 v142, s[10:11]
	s_add_u32 m0, s15, 0x18020
	s_add_u32 s10, s8, s2
	s_addc_u32 s11, s9, s3
	global_load_lds_dwordx4 v142, s[10:11]
	ds_read_b128 v[130:133], v156 offset:0
	ds_read_b128 v[148:151], v195 offset:0
	ds_read_b128 v[152:155], v195 offset:4096
	ds_read_b128 v[134:137], v156 offset:4096
	ds_read_b128 v[138:141], v156 offset:8192
	ds_read_b128 v[144:147], v156 offset:12288
